# v7 plus: small scalar-table loads of the mLSTM units no longer wait on their own round trip (P3 and P4)
# baseline (speedup 1.0000x reference)
; #define LAS __attribute__((address_space(3)))
; __device__ __forceinline__ void ml_loc_unit(LAS unsigned char* lds, const MixBufs& B, int b, int h, int seg, int tid) {
;     ...
;     const size_t sb = ((size_t)b * NCH) * 4 + h;
;     LAS float* SQ = (LAS float*)(lds + L_SQ); LAS float* WG = (LAS float*)(lds + L_WG); LAS float* WL = (LAS float*)(lds + L_WL);
;     const int cg = tid & 31, ts = tid >> 5;
;     ml_load_weights(WL, B, h, tid);
;     if (tid < 32) { SQ[2 * tid] = B.flast[sb + 4 * tid]; SQ[2 * tid + 1] = B.mloc[sb + 4 * tid]; }
.LBB0_475:
	s_or_b64 exec, exec, s[2:3]
	v_mov_b32_e32 v2, s25
	s_mov_b32 s3, 0
	v_readfirstlane_b32 s2, v2
	s_ashr_i32 s9, s8, 31
	v_mov_b32_e32 v79, 0
	s_bfe_i64 s[10:11], s[2:3], 0x80000
	v_cmp_gt_i32_e32 vcc, 32, v18
	s_and_saveexec_b64 s[2:3], vcc
	s_cbranch_execz .LBB0_477
	s_lshl_b64 s[4:5], s[8:9], 7
	s_add_u32 s4, s4, s10
	s_addc_u32 s5, s5, s11
	v_ashrrev_i32_e32 v21, 31, v20
	v_lshl_add_u64 v[2:3], s[4:5], 0, v[20:21]
	v_readlane_b32 s4, v240, 1
	v_lshlrev_b64 v[2:3], 2, v[2:3]
	v_readlane_b32 s5, v240, 2
	v_lshl_add_u32 v222, v18, 3, 0
	s_nop 0
	v_lshl_add_u64 v[4:5], s[4:5], 0, v[2:3]
	v_readlane_b32 s4, v240, 3
	v_readlane_b32 s5, v240, 4
	s_nop 1
	v_lshl_add_u64 v[2:3], s[4:5], 0, v[2:3]
	global_load_dword v220, v[4:5], off
	s_nop 0
	global_load_dword v221, v[2:3], off
	s_nop 0
	s_nop 0

; __device__ __forceinline__ void ml_loc_unit(LAS unsigned char* lds, const MixBufs& B, int b, int h, int seg, int tid) {
;     ...
;     if (tid < 32) { SQ[2 * tid] = B.flast[sb + 4 * tid]; SQ[2 * tid + 1] = B.mloc[sb + 4 * tid]; }
;     u32x2 xq[2][4]; v4u rv0[2], rv1[2]; float rwg[2] = {0.f, 0.f};
;     ...
;     MLL_PREFETCH(0, 8 * seg); MLL_PREFETCH(1, 8 * seg + 1);
;     __syncthreads();
;     float m = 0.f;
;     for (int n = 0; n < 8 * seg; ++n) { const float fl = SQ[2 * n], ml = SQ[2 * n + 1]; m = fmaxf(fl + m, ml); }
.LBB0_481:
	s_or_b64 exec, exec, s[16:17]
	v_cmp_gt_i32_e32 vcc, 32, v18
	s_and_saveexec_b64 s[20:21], vcc
	s_waitcnt vmcnt(14)
	ds_write_b64 v222, v[220:221] offset:35072
	s_mov_b64 exec, s[20:21]
	s_cmp_lt_i32 s24, 1
	s_waitcnt lgkmcnt(0)
	s_barrier
	s_cbranch_scc1 .LBB0_484
	s_add_i32 s14, 0, 0x8900
	v_mov_b32_e32 v87, 0
	s_mov_b32 s15, s4

; #define LAS __attribute__((address_space(3)))
; __device__ __forceinline__ void ml_out_unit(LAS unsigned char* lds, const MixBufs& B, int b, int h, int seg, int tid) {
;     ...
;     const size_t sb = ((size_t)b * NCH) * 4 + h;
;     LAS float* SQ = (LAS float*)(lds + O_SQ); LAS float* LI = (LAS float*)(lds + O_LI); LAS float* FC = (LAS float*)(lds + O_FC); LAS float* WG = (LAS float*)(lds + O_WG);
;     LAS float* GN = (LAS float*)(lds + O_GN); LAS float* SK = (LAS float*)(lds + O_SK); LAS float* WL = (LAS float*)(lds + O_WL);
;     if (tid < 32) { SQ[2 * tid] = B.flast[sb + 4 * tid]; SQ[2 * tid + 1] = B.mloc[sb + 4 * tid]; }
;     if (tid >= 64 && tid < 192) { GN[tid - 64] = B.g_ml_norm[h * 128 + tid - 64]; SK[tid - 64] = B.ml_skip[h * 128 + tid - 64]; }
;     ml_load_weights(WL, B, h, tid);
;     u32x2 xr[4]; v4u rv0, rv1; float rwg = 0.f, rli = 0.f, rfc = 0.f;
.LBB0_596:
	s_bfe_u32 s8, s72, 0x20002
	s_and_b32 s25, s71, 3
	s_lshl_b32 s10, s8, 8
	s_ashr_i32 s6, s72, 5
	s_and_b32 s24, s72, 3
	s_bitcmp1_b32 s72, 4
	s_mov_b32 s11, s9
	s_cbranch_scc0 .LBB0_620
	v_mov_b32_e32 v166, v0
	s_ashr_i32 s7, s6, 31
	v_readfirstlane_b32 s20, v166
	v_cmp_gt_i32_e32 vcc, 32, v166
	v_lshlrev_b32_e32 v187, 2, v166
	s_and_saveexec_b64 s[2:3], vcc
	s_cbranch_execz .LBB0_599
	s_lshl_b64 s[4:5], s[6:7], 7
	v_lshlrev_b32_e32 v4, 2, v166
	s_or_b64 s[4:5], s[4:5], s[8:9]
	v_ashrrev_i32_e32 v5, 31, v4
	v_lshl_add_u64 v[4:5], s[4:5], 0, v[4:5]
	v_readlane_b32 s4, v240, 1
	v_lshlrev_b64 v[4:5], 2, v[4:5]
	v_readlane_b32 s5, v240, 2
	v_lshl_add_u32 v2, v166, 3, 0
	v_add_u32_e32 v222, 0x22700, v2
	v_lshl_add_u64 v[6:7], s[4:5], 0, v[4:5]
	v_readlane_b32 s4, v240, 3
	v_readlane_b32 s5, v240, 4
	s_nop 1
	v_lshl_add_u64 v[4:5], s[4:5], 0, v[4:5]
	global_load_dword v220, v[6:7], off
	s_nop 0
	global_load_dword v221, v[4:5], off
	s_nop 0
	s_nop 0
.LBB0_599:
	s_or_b64 exec, exec, s[2:3]
	v_subrev_u32_e32 v4, 64, v166
	v_cmp_gt_u32_e32 vcc, s69, v4
	s_and_saveexec_b64 s[2:3], vcc
	s_cbranch_execz .LBB0_601
	v_lshl_add_u32 v2, s8, 7, v4
	v_readlane_b32 s36, v241, 2
	v_lshlrev_b64 v[6:7], 2, v[2:3]
	v_readlane_b32 s46, v241, 12
	v_readlane_b32 s47, v241, 13
	v_readlane_b32 s48, v241, 14
	v_readlane_b32 s49, v241, 15
	v_lshl_add_u32 v2, v4, 2, 0
	v_lshl_add_u64 v[4:5], s[46:47], 0, v[6:7]
	v_lshl_add_u64 v[8:9], s[48:49], 0, v[6:7]
	global_load_dword v223, v[8:9], off
	v_add_u32_e32 v225, 0x22800, v2
	global_load_dword v224, v[4:5], off
	v_add_u32_e32 v226, 0x22a00, v2
	v_readlane_b32 s37, v241, 3
	v_readlane_b32 s38, v241, 4
	v_readlane_b32 s39, v241, 5
	v_readlane_b32 s40, v241, 6
	v_readlane_b32 s41, v241, 7
	v_readlane_b32 s42, v241, 8
	v_readlane_b32 s43, v241, 9
	v_readlane_b32 s44, v241, 10
	v_readlane_b32 s45, v241, 11
	v_readlane_b32 s50, v241, 16
	v_readlane_b32 s51, v241, 17
	s_nop 0
	s_nop 0
	s_nop 0
	s_nop 0

; __device__ __forceinline__ float fexp(float x) { return __builtin_amdgcn_exp2f(x * LOG2E); }
; __device__ __forceinline__ void ml_out_unit(LAS unsigned char* lds, const MixBufs& B, int b, int h, int seg, int tid) {
;     ...
;     if (tid < 32) { SQ[2 * tid] = B.flast[sb + 4 * tid]; SQ[2 * tid + 1] = B.mloc[sb + 4 * tid]; }
;     if (tid >= 64 && tid < 192) { GN[tid - 64] = B.g_ml_norm[h * 128 + tid - 64]; SK[tid - 64] = B.ml_skip[h * 128 + tid - 64]; }
;     ml_load_weights(WL, B, h, tid);
;     u32x2 xr[4]; v4u rv0, rv1; float rwg = 0.f, rli = 0.f, rfc = 0.f;
;     const int vr = tid >> 4, vc = tid & 15;
;     ...
;     __syncthreads();
;     float m = 0.f, G0 = 1.f, G1 = 1.f, G2 = 1.f;
;     for (int i = 0; i < seg; ++i) {
;         float gacc = 1.f;
;         for (int n = 8 * i; n < 8 * i + 8; ++n) { const float fl = SQ[2 * n], ml = SQ[2 * n + 1], mn = fmaxf(fl + m, ml); gacc *= fexp(fl + m - mn); m = mn; }
;         if (i == 0) G0 = gacc; else if (i == 1) G1 = gacc; else G2 = gacc; }
.LBB0_621:
	s_or_b64 exec, exec, s[2:3]
	s_waitcnt vmcnt(0)
	v_cmp_gt_i32_e32 vcc, 32, v166
	s_and_saveexec_b64 s[14:15], vcc
	ds_write_b64 v222, v[220:221]
	s_mov_b64 exec, s[14:15]
	v_subrev_u32_e32 v227, 64, v166
	v_cmp_gt_u32_e32 vcc, s69, v227
	s_and_saveexec_b64 s[14:15], vcc
	ds_write_b32 v225, v223
	ds_write_b32 v226, v224
	s_mov_b64 exec, s[14:15]
	s_lshl_b32 s13, s25, 6
	s_cmp_lg_u32 s24, 0
	s_cselect_b64 s[2:3], -1, 0
	s_cmp_eq_u32 s24, 0
	s_waitcnt lgkmcnt(0)
	s_barrier
	s_cbranch_scc1 .LBB0_631
	s_mov_b32 s12, 0
	v_mov_b32_e32 v186, 0
	v_mov_b32_e32 v2, 1.0
	v_mov_b32_e32 v4, 1.0
	v_mov_b32_e32 v78, 1.0
	s_mov_b32 s14, 0
	s_branch .LBB0_624
